# LayerNorm loops: gamma/beta hoisted out of row loop, both row halves loaded together, store-draining waits removed, dead fp8 store of the post-FFN1 LN dropped; conv loop pipelined
# speedup vs baseline: 1.0751x; 1.0210x over previous
; __device__ __forceinline__ unsigned cvt_pk_bf16(float lo, float hi) { unsigned r; asm("v_cvt_pk_bf16_f32 %0, %1, %2" : "=v"(r) : "v"(lo), "v"(hi)); return r; }
; __device__ __forceinline__ float siluf(float x) { return x * __builtin_amdgcn_rcpf(1.0f + __expf(-x)); }
; __device__ __forceinline__ void conv_phase(ArgsP a_) { const ArgsP a = a_;
;     ...
;         for (int j = 0; j < nrow; ++j) {
;             const u32x4 x = *(const u32x4*)(XBC + (size_t)(row0 + j) * 4096 + col); float cur[8];
;             cur[0] = __uint_as_float(x.x << 16); cur[1] = __uint_as_float(x.x & 0xffff0000u); cur[2] = __uint_as_float(x.y << 16); cur[3] = __uint_as_float(x.y & 0xffff0000u);
;             cur[4] = __uint_as_float(x.z << 16); cur[5] = __uint_as_float(x.z & 0xffff0000u); cur[6] = __uint_as_float(x.w << 16); cur[7] = __uint_as_float(x.w & 0xffff0000u);
;             float y[8];
; #pragma unroll
;             for (int e = 0; e < 8; ++e) { y[e] = siluf(bs[e] + w[0][e] * r[0][e] + w[1][e] * r[1][e] + w[2][e] * r[2][e] + w[3][e] * cur[e]); r[0][e] = r[1][e]; r[1][e] = r[2][e]; r[2][e] = cur[e]; }
;             *(u32x4*)(XC + (size_t)(row0 + j) * 4096 + col) = (u32x4){cvt_pk_bf16(y[0], y[1]), cvt_pk_bf16(y[2], y[3]), cvt_pk_bf16(y[4], y[5]), cvt_pk_bf16(y[6], y[7])};
;         }
.LBB0_54:
	s_or_b64 exec, exec, s[34:35]
	v_lshl_add_u64 v[80:81], s[24:25], 0, v[16:17]
	s_waitcnt vmcnt(0)
	v_mov_b32_e32 v82, v52
	s_waitcnt vmcnt(4)
	v_mov_b32_e32 v83, v14
	v_mov_b32_e32 v14, v53
	s_waitcnt vmcnt(3)
	v_mov_b32_e32 v52, v56
	v_mov_b32_e32 v53, v6
	v_mov_b32_e32 v6, v57
	v_mov_b32_e32 v56, v50
	v_mov_b32_e32 v57, v12
	v_mov_b32_e32 v12, v51
	v_mov_b32_e32 v50, v54
	v_mov_b32_e32 v51, v4
	v_mov_b32_e32 v4, v55
	v_mov_b32_e32 v54, v44
	v_mov_b32_e32 v55, v10
	v_mov_b32_e32 v10, v45
	s_waitcnt vmcnt(1)
	v_mov_b32_e32 v44, v48
	v_mov_b32_e32 v45, v2
	v_mov_b32_e32 v2, v49
	v_mov_b32_e32 v48, v42
	v_mov_b32_e32 v49, v8
	v_mov_b32_e32 v8, v43
	v_mov_b32_e32 v42, v46
	v_mov_b32_e32 v43, v0
	v_mov_b32_e32 v0, v47
	s_mov_b64 s[34:35], 0
	v_ashrrev_i32_e32 v61, 31, v60
	v_lshlrev_b64 v[212:213], 13, v[60:61]
	v_lshl_add_u64 v[212:213], v[62:63], 0, v[212:213]
	global_load_dwordx4 v[202:205], v[212:213], off
	s_waitcnt vmcnt(0)
.LBB0_55:
	v_ashrrev_i32_e32 v61, 31, v60
	v_lshlrev_b64 v[46:47], 13, v[60:61]
	v_add_u32_e32 v212, 1, v60
	v_ashrrev_i32_e32 v213, 31, v212
	v_lshlrev_b64 v[212:213], 13, v[212:213]
	v_lshl_add_u64 v[212:213], v[62:63], 0, v[212:213]
	s_waitcnt vmcnt(1)
	v_mov_b32_e32 v86, v202
	v_mov_b32_e32 v87, v203
	v_mov_b32_e32 v88, v204
	v_mov_b32_e32 v89, v205
	global_load_dwordx4 v[202:205], v[212:213], off
	v_add_u32_e32 v84, -1, v84
	v_cmp_eq_u32_e32 vcc, 0, v84
	v_lshl_add_u64 v[46:47], v[80:81], 0, v[46:47]
	v_add_u32_e32 v60, 1, v60
	s_or_b64 s[34:35], vcc, s[34:35]
	v_lshlrev_b32_e32 v35, 16, v86
	v_and_b32_e32 v73, 0xffff0000, v86
	v_lshlrev_b32_e32 v37, 16, v87
	v_and_b32_e32 v75, 0xffff0000, v87
	v_pk_mul_f32 v[86:87], v[42:43], v[26:27]
	v_lshlrev_b32_e32 v39, 16, v88
	v_add_f32_e32 v16, v22, v86
	v_add_f32_e32 v16, v87, v16
	v_pk_mul_f32 v[86:87], v[48:49], v[34:35]
	v_and_b32_e32 v77, 0xffff0000, v88
	v_add_f32_e32 v16, v86, v16
	v_add_f32_e32 v16, v16, v87
	v_mul_f32_e32 v26, 0xbfb8aa3b, v16
	v_exp_f32_e32 v26, v26
	v_pk_mul_f32 v[86:87], v[0:1], v[64:65]
	v_lshlrev_b32_e32 v41, 16, v89
	v_and_b32_e32 v79, 0xffff0000, v89
	v_add_f32_e32 v26, 1.0, v26
	v_rcp_f32_e32 v26, v26
	s_nop 0
	v_mul_f32_e32 v16, v16, v26
	v_add_f32_e32 v26, v23, v86
	v_add_f32_e32 v26, v87, v26
	v_pk_mul_f32 v[86:87], v[8:9], v[72:73]
	s_nop 0
	v_add_f32_e32 v26, v86, v26
	v_add_f32_e32 v26, v26, v87
	v_mul_f32_e32 v61, 0xbfb8aa3b, v26
	v_exp_f32_e32 v61, v61
	v_pk_mul_f32 v[86:87], v[44:45], v[28:29]
	v_add_f32_e32 v61, 1.0, v61
	v_rcp_f32_e32 v61, v61
	v_add_f32_e32 v28, v24, v86
	v_add_f32_e32 v28, v87, v28
	v_pk_mul_f32 v[86:87], v[54:55], v[36:37]
	v_mul_f32_e32 v26, v26, v61
	v_add_f32_e32 v28, v86, v28
	v_add_f32_e32 v28, v28, v87
	v_mul_f32_e32 v61, 0xbfb8aa3b, v28
	v_exp_f32_e32 v61, v61
	v_pk_mul_f32 v[86:87], v[2:3], v[66:67]
	v_add_f32_e32 v61, 1.0, v61
	v_rcp_f32_e32 v61, v61
	s_nop 0
	v_mul_f32_e32 v28, v28, v61
	v_add_f32_e32 v61, v25, v86
	v_add_f32_e32 v61, v87, v61
	v_pk_mul_f32 v[86:87], v[10:11], v[74:75]
	s_nop 0
	v_add_f32_e32 v61, v86, v61
	v_add_f32_e32 v61, v61, v87
	v_mul_f32_e32 v64, 0xbfb8aa3b, v61
	v_exp_f32_e32 v64, v64
	v_pk_mul_f32 v[86:87], v[50:51], v[30:31]
	v_add_f32_e32 v64, 1.0, v64
	v_rcp_f32_e32 v64, v64
	v_add_f32_e32 v30, v18, v86
	v_add_f32_e32 v30, v87, v30
	v_pk_mul_f32 v[86:87], v[56:57], v[38:39]
	v_mul_f32_e32 v61, v61, v64
	v_add_f32_e32 v30, v86, v30
	v_add_f32_e32 v30, v30, v87
	v_mul_f32_e32 v64, 0xbfb8aa3b, v30
	v_exp_f32_e32 v64, v64
	v_pk_mul_f32 v[86:87], v[4:5], v[68:69]
	v_add_f32_e32 v64, 1.0, v64
	v_rcp_f32_e32 v64, v64
	s_nop 0
	v_mul_f32_e32 v30, v30, v64
	v_add_f32_e32 v64, v19, v86
	v_add_f32_e32 v64, v87, v64
	v_pk_mul_f32 v[86:87], v[12:13], v[76:77]
	s_nop 0
	v_add_f32_e32 v64, v86, v64
	v_add_f32_e32 v64, v64, v87
	v_mul_f32_e32 v66, 0xbfb8aa3b, v64
	v_exp_f32_e32 v66, v66
	v_pk_mul_f32 v[86:87], v[52:53], v[32:33]
	v_add_f32_e32 v66, 1.0, v66
	v_rcp_f32_e32 v66, v66
	v_add_f32_e32 v32, v20, v86
	v_add_f32_e32 v32, v87, v32
	v_pk_mul_f32 v[86:87], v[82:83], v[40:41]
	v_mul_f32_e32 v64, v64, v66
	v_add_f32_e32 v32, v86, v32
	v_add_f32_e32 v32, v32, v87
	v_mul_f32_e32 v66, 0xbfb8aa3b, v32
	v_exp_f32_e32 v66, v66
	v_pk_mul_f32 v[86:87], v[6:7], v[70:71]
	v_cvt_pk_bf16_f32 v88, v30, v64
	v_mov_b32_e32 v70, v71
	v_add_f32_e32 v66, 1.0, v66
	v_rcp_f32_e32 v66, v66
	v_mov_b32_e32 v71, v78
	v_mov_b32_e32 v30, v31
	v_mov_b32_e32 v31, v38
	v_mul_f32_e32 v32, v32, v66
	v_add_f32_e32 v66, v21, v86
	v_add_f32_e32 v66, v87, v66
	v_pk_mul_f32 v[86:87], v[14:15], v[78:79]
	v_mov_b32_e32 v78, v79
	v_add_f32_e32 v66, v86, v66
	v_add_f32_e32 v66, v66, v87
	v_mul_f32_e32 v68, 0xbfb8aa3b, v66
	v_exp_f32_e32 v68, v68
	v_cvt_pk_bf16_f32 v86, v16, v26
	v_cvt_pk_bf16_f32 v87, v28, v61
	v_mov_b32_e32 v38, v39
	v_add_f32_e32 v68, 1.0, v68
	v_rcp_f32_e32 v68, v68
	v_mov_b32_e32 v28, v29
	v_mov_b32_e32 v29, v36
	v_mov_b32_e32 v36, v37
	v_mul_f32_e32 v66, v66, v68
	v_cvt_pk_bf16_f32 v89, v32, v66
	v_mov_b32_e32 v32, v33
	v_mov_b32_e32 v33, v40
	v_mov_b32_e32 v40, v41
	v_mov_b32_e32 v68, v69
	v_mov_b32_e32 v69, v76
	v_mov_b32_e32 v76, v77
	v_mov_b32_e32 v66, v67
	v_mov_b32_e32 v67, v74
	v_mov_b32_e32 v74, v75
	v_mov_b32_e32 v26, v27
	v_mov_b32_e32 v27, v34
	v_mov_b32_e32 v34, v35
	v_mov_b32_e32 v64, v65
	v_mov_b32_e32 v65, v72
	v_mov_b32_e32 v72, v73
	global_store_dwordx4 v[46:47], v[86:89], off
	s_andn2_b64 exec, exec, s[34:35]
	s_cbranch_execnz .LBB0_55
	s_or_b64 exec, exec, s[34:35]
	v_readlane_b32 s34, v253, 4
	v_readlane_b32 s35, v253, 5
	s_nop 1
	v_lshl_add_u64 v[58:59], v[58:59], 0, s[34:35]
	s_mov_b64 s[34:35], 0x90fff
	v_cmp_lt_u64_e32 vcc, s[34:35], v[58:59]
	s_or_b64 s[26:27], vcc, s[26:27]
	s_andn2_b64 exec, exec, s[26:27]
	s_cbranch_execnz .LBB0_32

; __device__ __forceinline__ int TID() { int t = threadIdx.x; asm volatile("" : "+v"(t)); return t; }
; __device__ __forceinline__ int BID() { int t = blockIdx.x; asm volatile("" : "+s"(t)); return t; }
; __device__ __forceinline__ void ln_phase(ArgsP a_, int lnidx, float cs, bool final_) { const ArgsP a = a_;
;     const int lane = TID() & 63, wv = TID() >> 6; const int gw = BID() * 8 + wv, nw = gridDim.x * 8;
;     bf16_t* HB = (bf16_t*)(a->ws + B_HB); const bf16_t* P0 = (const bf16_t*)(a->ws + B_PARTB); const bf16_t* P1 = P0 + (size_t)MP * 1024;
;     const float* g = AIN(7) + (size_t)lnidx * 1024; const float* bb = AIN(8) + (size_t)lnidx * 1024;
;     ...
;         for (int q = 0; q < 2; ++q) { const int cc = q * 512 + lane * 8; const f32x4 g0 = *(const f32x4*)(g + cc), g1 = *(const f32x4*)(g + cc + 4), b0 = *(const f32x4*)(bb + cc), b1 = *(const f32x4*)(bb + cc + 4);
.LBB0_59:
	s_andn2_b64 vcc, exec, s[18:19]
	s_cbranch_vccnz .LBB0_89
	v_mov_b32_e32 v0, v186
	v_mov_b32_e32 v1, v186
	s_mov_b32 s13, s93
	v_ashrrev_i32_e32 v1, 6, v1
	s_nop 0
	v_lshl_add_u32 v12, s13, 3, v1
	s_movk_i32 s13, 0x4480
	v_cmp_gt_i32_e32 vcc, s13, v12
	s_and_saveexec_b64 s[18:19], vcc
	s_cbranch_execz .LBB0_88
	v_lshlrev_b32_e32 v0, 3, v0
	v_and_b32_e32 v14, 0x1f8, v0
	v_and_b32_e32 v0, 64, v188
	v_add_u32_e32 v0, 64, v0
	v_xor_b32_e32 v1, 32, v188
	v_cmp_lt_i32_e32 vcc, v1, v0
	v_readlane_b32 s13, v254, 60
	s_cmp_eq_u32 s13, 3
	v_cndmask_b32_e32 v1, v188, v1, vcc
	v_lshlrev_b32_e32 v36, 2, v1
	v_xor_b32_e32 v1, 16, v188
	v_cmp_lt_i32_e32 vcc, v1, v0
	s_cselect_b64 s[22:23], -1, 0
	s_cmp_lg_u32 s13, 3
	v_cndmask_b32_e32 v1, v188, v1, vcc
	s_cselect_b64 s[24:25], -1, 0
	s_waitcnt lgkmcnt(0)
	s_add_u32 s26, s2, 0xfd80000
	v_lshlrev_b32_e32 v37, 2, v1
	v_xor_b32_e32 v1, 8, v188
	s_addc_u32 s27, s3, 0
	v_cmp_lt_i32_e32 vcc, v1, v0
	s_add_u32 s34, s2, 0xb880000
	s_load_dwordx4 s[44:47], s[0:1], 0x38
	v_cndmask_b32_e32 v1, v188, v1, vcc
	s_addc_u32 s35, s3, 0
	v_lshlrev_b32_e32 v38, 2, v1
	v_xor_b32_e32 v1, 4, v188
	s_add_u32 s42, s2, 0xdb00000
	s_mul_i32 s13, s13, 3
	v_cmp_lt_i32_e32 vcc, v1, v0
	s_addc_u32 s43, s3, 0
	s_add_i32 s40, s13, 2
	s_mov_b32 s41, s12
	v_cndmask_b32_e32 v1, v188, v1, vcc
	s_lshl_b64 s[40:41], s[40:41], 12
	v_lshlrev_b32_e32 v39, 2, v1
	v_xor_b32_e32 v1, 2, v188
	s_waitcnt lgkmcnt(0)
	s_add_u32 s46, s46, s40
	v_cmp_lt_i32_e32 vcc, v1, v0
	s_addc_u32 s47, s47, s41
	s_add_u32 s40, s44, s40
	v_cndmask_b32_e32 v1, v188, v1, vcc
	v_lshlrev_b32_e32 v40, 2, v1
	v_xor_b32_e32 v1, 1, v188
	s_addc_u32 s41, s45, s41
	v_cmp_lt_i32_e32 vcc, v1, v0
	s_add_u32 s44, s2, 0x3752b700
	v_lshlrev_b32_e32 v16, 2, v14
	v_cndmask_b32_e32 v0, v188, v1, vcc
	v_mov_b32_e32 v15, v17
	v_lshlrev_b32_e32 v41, 2, v0
	s_addc_u32 s45, s3, 0
	v_lshl_add_u64 v[18:19], s[40:41], 0, v[16:17]
	v_lshl_add_u64 v[20:21], s[46:47], 0, v[16:17]
	s_mov_b64 s[46:47], 0
	global_load_dwordx4 v[214:217], v[18:19], off offset:16
	global_load_dwordx4 v[218:221], v[18:19], off
	global_load_dwordx4 v[222:225], v[20:21], off offset:16
	global_load_dwordx4 v[226:229], v[20:21], off
	global_load_dwordx4 v[230:233], v[18:19], off offset:2064
	global_load_dwordx4 v[234:237], v[18:19], off offset:2048
	global_load_dwordx4 v[238:241], v[20:21], off offset:2048
	global_load_dwordx4 v[242:245], v[20:21], off offset:2064
	s_waitcnt vmcnt(0)
	s_branch .LBB0_65

; __device__ __forceinline__ unsigned cvt_pk_bf16(float lo, float hi) { unsigned r; asm("v_cvt_pk_bf16_f32 %0, %1, %2" : "=v"(r) : "v"(lo), "v"(hi)); return r; }
; __device__ __forceinline__ unsigned pk_fp8x4(float a, float b, float c, float d) { int w = 0; w = __builtin_amdgcn_cvt_pk_fp8_f32(clamp448(a), clamp448(b), w, false); w = __builtin_amdgcn_cvt_pk_fp8_f32(clamp448(c), clamp448(d), w, true); return (unsigned)w; }
; __device__ __forceinline__ void ln_phase(ArgsP a_, int lnidx, float cs, bool final_) { const ArgsP a = a_;
;     ...
;         for (int q = 0; q < 2; ++q) { const int cc = q * 512 + lane * 8; const f32x4 g0 = *(const f32x4*)(g + cc), g1 = *(const f32x4*)(g + cc + 4), b0 = *(const f32x4*)(bb + cc), b1 = *(const f32x4*)(bb + cc + 4);
;             f32x4 o0, o1;
; #pragma unroll
;             for (int e = 0; e < 4; ++e) { o0[e] = (z[q * 8 + e] - mean) * rstd * g0[e] + b0[e]; o1[e] = (z[q * 8 + 4 + e] - mean) * rstd * g1[e] + b1[e]; }
;             if (final_) { if (yo) { *(f32x4*)(yo + cc) = o0; *(f32x4*)(yo + cc + 4) = o1; } }
;             else { *(u32x4*)(HB + (size_t)row * 1024 + cc) = (u32x4){cvt_pk_bf16(o0[0], o0[1]), cvt_pk_bf16(o0[2], o0[3]), cvt_pk_bf16(o1[0], o1[1]), cvt_pk_bf16(o1[2], o1[3])};
;                    *(u32x2*)(a->ws + B_HB8 + (size_t)row * 1024 + cc) = (u32x2){pk_fp8x4(o0[0] * SC_H, o0[1] * SC_H, o0[2] * SC_H, o0[3] * SC_H), pk_fp8x4(o1[0] * SC_H, o1[1] * SC_H, o1[2] * SC_H, o1[3] * SC_H)}; } }
.LBB0_73:
	s_waitcnt lgkmcnt(0)
	v_add_f32_e32 v13, v13, v32
	v_fmamk_f32 v13, v13, 0x3a800000, v187
	v_cmp_gt_f32_e32 vcc, s31, v13
	v_mul_f32_e32 v16, 0x4b800000, v13
	v_lshl_add_u64 v[30:31], v[22:23], 1, s[26:27]
	v_cndmask_b32_e32 v13, v13, v16, vcc
	v_rsq_f32_e32 v13, v13
	v_lshl_add_u64 v[22:23], s[44:45], 0, v[22:23]
	v_cmp_ne_u64_e64 s[40:41], 0, v[8:9]
	s_mov_b64 s[48:49], -1
	v_mul_f32_e32 v16, 0x45800000, v13
	v_cndmask_b32_e32 v32, v13, v16, vcc
	v_pk_mul_f32 v[0:1], v[0:1], v[32:33] op_sel_hi:[1,0]
	v_pk_mul_f32 v[34:35], v[4:5], v[32:33] op_sel_hi:[1,0]
	v_pk_mul_f32 v[6:7], v[6:7], v[32:33] op_sel_hi:[1,0]
	v_pk_mul_f32 v[2:3], v[2:3], v[32:33] op_sel_hi:[1,0]
	s_and_b64 vcc, exec, s[24:25]
	v_lshl_add_u64 v[22:23], v[22:23], 0, v[14:15]
	v_pk_fma_f32 v[2:3], v[2:3], v[216:217], v[224:225]
	v_pk_fma_f32 v[4:5], v[0:1], v[218:219], v[226:227]
	v_pk_fma_f32 v[0:1], v[34:35], v[214:215], v[222:223]
	v_pk_fma_f32 v[6:7], v[6:7], v[220:221], v[228:229]
	v_lshlrev_b32_e32 v34, 1, v14
	s_cbranch_vccz .LBB0_75
	v_mov_b32_e32 v35, v17
	v_cvt_pk_bf16_f32 v42, v4, v5
	v_lshl_add_u64 v[46:47], v[30:31], 0, v[34:35]
	v_mul_f32_e32 v13, 0x4134cccd, v4
	v_mul_f32_e32 v16, 0x4134cccd, v5
	v_cvt_pk_bf16_f32 v43, v6, v7
	v_cvt_pk_bf16_f32 v44, v0, v1
	v_cvt_pk_bf16_f32 v45, v2, v3
	global_store_dwordx4 v[46:47], v[42:45], off
	v_med3_f32 v13, v13, s17, v190
	v_med3_f32 v16, v16, s17, v190
	v_mov_b32_e32 v42, v17
	v_cvt_pk_fp8_f32 v42, v13, v16
	v_mul_f32_e32 v33, 0x4134cccd, v6
	v_mul_f32_e32 v35, 0x4134cccd, v7
	v_med3_f32 v13, v33, s17, v190
	v_med3_f32 v16, v35, s17, v190
	v_cvt_pk_fp8_f32 v42, v13, v16 op_sel:[0,0,1]
	v_mul_f32_e32 v13, 0x4134cccd, v0
	v_mul_f32_e32 v16, 0x4134cccd, v1
	v_med3_f32 v13, v13, s17, v190
	v_med3_f32 v16, v16, s17, v190
	v_mov_b32_e32 v43, v17
	v_cvt_pk_fp8_f32 v43, v13, v16
	v_mul_f32_e32 v33, 0x4134cccd, v2
	v_mul_f32_e32 v35, 0x4134cccd, v3
	v_med3_f32 v13, v33, s17, v190
	v_med3_f32 v16, v35, s17, v190
	v_cvt_pk_fp8_f32 v43, v13, v16 op_sel:[0,0,1]
	s_mov_b64 s[48:49], 0
	global_store_dwordx2 v[22:23], v[42:43], off

; __device__ __forceinline__ unsigned cvt_pk_bf16(float lo, float hi) { unsigned r; asm("v_cvt_pk_bf16_f32 %0, %1, %2" : "=v"(r) : "v"(lo), "v"(hi)); return r; }
; __device__ __forceinline__ unsigned pk_fp8x4(float a, float b, float c, float d) { int w = 0; w = __builtin_amdgcn_cvt_pk_fp8_f32(clamp448(a), clamp448(b), w, false); w = __builtin_amdgcn_cvt_pk_fp8_f32(clamp448(c), clamp448(d), w, true); return (unsigned)w; }
; __device__ __forceinline__ void ln_phase(ArgsP a_, int lnidx, float cs, bool final_) { const ArgsP a = a_;
;     ...
;         for (int q = 0; q < 2; ++q) { const int cc = q * 512 + lane * 8; const f32x4 g0 = *(const f32x4*)(g + cc), g1 = *(const f32x4*)(g + cc + 4), b0 = *(const f32x4*)(bb + cc), b1 = *(const f32x4*)(bb + cc + 4);
;             f32x4 o0, o1;
; #pragma unroll
;             for (int e = 0; e < 4; ++e) { o0[e] = (z[q * 8 + e] - mean) * rstd * g0[e] + b0[e]; o1[e] = (z[q * 8 + 4 + e] - mean) * rstd * g1[e] + b1[e]; }
;             if (final_) { if (yo) { *(f32x4*)(yo + cc) = o0; *(f32x4*)(yo + cc + 4) = o1; } }
;             else { *(u32x4*)(HB + (size_t)row * 1024 + cc) = (u32x4){cvt_pk_bf16(o0[0], o0[1]), cvt_pk_bf16(o0[2], o0[3]), cvt_pk_bf16(o1[0], o1[1]), cvt_pk_bf16(o1[2], o1[3])};
;                    *(u32x2*)(a->ws + B_HB8 + (size_t)row * 1024 + cc) = (u32x2){pk_fp8x4(o0[0] * SC_H, o0[1] * SC_H, o0[2] * SC_H, o0[3] * SC_H), pk_fp8x4(o1[0] * SC_H, o1[1] * SC_H, o1[2] * SC_H, o1[3] * SC_H)}; } }
.LBB0_79:
	v_mov_b32_e32 v33, v32
	v_pk_mul_f32 v[10:11], v[10:11], v[32:33]
	v_pk_mul_f32 v[24:25], v[24:25], v[32:33]
	v_pk_mul_f32 v[28:29], v[28:29], v[32:33]
	v_pk_mul_f32 v[26:27], v[26:27], v[32:33]
	s_andn2_b64 vcc, exec, s[24:25]
	s_mov_b64 s[48:49], -1
	v_pk_fma_f32 v[4:5], v[10:11], v[234:235], v[238:239]
	v_pk_fma_f32 v[0:1], v[24:25], v[230:231], v[242:243]
	v_pk_fma_f32 v[6:7], v[28:29], v[236:237], v[240:241]
	v_pk_fma_f32 v[2:3], v[26:27], v[232:233], v[244:245]
	s_cbranch_vccnz .LBB0_81
	v_mov_b32_e32 v35, v17
	v_lshl_add_u64 v[10:11], v[30:31], 0, v[34:35]
	v_cvt_pk_bf16_f32 v24, v4, v5
	v_cvt_pk_bf16_f32 v25, v6, v7
	v_cvt_pk_bf16_f32 v26, v0, v1
	v_cvt_pk_bf16_f32 v27, v2, v3
	global_store_dwordx4 v[10:11], v[24:27], off offset:1024
	v_mul_f32_e32 v10, 0x4134cccd, v4
	v_mul_f32_e32 v11, 0x4134cccd, v5
	v_med3_f32 v24, v10, s17, v190
	v_med3_f32 v11, v11, s17, v190
	v_mov_b32_e32 v10, v17
	v_cvt_pk_fp8_f32 v10, v24, v11
	v_mul_f32_e32 v13, 0x4134cccd, v6
	v_mul_f32_e32 v16, 0x4134cccd, v7
	v_med3_f32 v11, v13, s17, v190
	v_med3_f32 v13, v16, s17, v190
	v_cvt_pk_fp8_f32 v10, v11, v13 op_sel:[0,0,1]
	v_mul_f32_e32 v11, 0x4134cccd, v0
	v_mul_f32_e32 v13, 0x4134cccd, v1
	v_med3_f32 v25, v11, s17, v190
	v_med3_f32 v13, v13, s17, v190
	v_mov_b32_e32 v11, v17
	v_cvt_pk_fp8_f32 v11, v25, v13
	v_mul_f32_e32 v16, 0x4134cccd, v2
	v_mul_f32_e32 v24, 0x4134cccd, v3
	v_med3_f32 v13, v16, s17, v190
	v_med3_f32 v16, v24, s17, v190
	v_cvt_pk_fp8_f32 v11, v13, v16 op_sel:[0,0,1]
	s_mov_b64 s[48:49], 0
	global_store_dwordx2 v[22:23], v[10:11], off offset:512

; __device__ __forceinline__ void ln_phase(ArgsP a_, int lnidx, float cs, bool final_) { const ArgsP a = a_;
;     ...
;     for (int row = gw; row < M_; row += nw) {
;         float z[16]; float s = 0.f;
; #pragma unroll
;         for (int q = 0; q < 2; ++q) { const size_t o = (size_t)row * 1024 + q * 512 + lane * 8; const u32x4 h = *(const u32x4*)(HB + o), p0 = *(const u32x4*)(P0 + o), p1 = *(const u32x4*)(P1 + o);
; #pragma unroll
;             for (int e = 0; e < 4; ++e) { const unsigned hh = h[e], a0 = p0[e], a1 = p1[e];
;                 z[q * 8 + 2 * e] = __uint_as_float(hh << 16) * ALPHA + (__uint_as_float(a0 << 16) + __uint_as_float(a1 << 16)) * cs;
;                 z[q * 8 + 2 * e + 1] = __uint_as_float(hh & 0xffff0000u) * ALPHA + (__uint_as_float(a0 & 0xffff0000u) + __uint_as_float(a1 & 0xffff0000u)) * cs; } }
.LBB0_91:
	v_writelane_b32 v255, s22, 1
	s_and_b64 vcc, exec, s[18:19]
	s_nop 0
	v_writelane_b32 v255, s23, 2
	s_cbranch_vccz .LBB0_99
	v_readlane_b32 s13, v254, 61
	s_cmp_gt_i32 s13, 6
	s_cbranch_scc0 .LBB0_101
	s_cmp_lt_i32 s13, 8
	s_mov_b64 s[56:57], -1
	s_cbranch_scc0 .LBB0_98
	v_mov_b32_e32 v10, v186
	v_mov_b32_e32 v0, v186
	s_mov_b32 s13, s93
	v_ashrrev_i32_e32 v0, 6, v0
	s_nop 0
	v_lshl_add_u32 v0, s13, 3, v0
	s_movk_i32 s13, 0x4480
	v_cmp_gt_i32_e32 vcc, s13, v0
	s_and_saveexec_b64 s[18:19], vcc
	s_mov_b32 s34, 0x3fd744fd
	v_readlane_b32 s42, v254, 49
	v_readlane_b32 s44, v254, 51
	s_mov_b32 s35, 0.5
	s_movk_i32 s40, 0x447f
	s_mov_b32 s41, 0x3752b000
	v_readlane_b32 s43, v254, 50
	v_readlane_b32 s45, v254, 52
	s_cbranch_execz .LBB0_97
	v_lshlrev_b32_e32 v1, 3, v10
	v_and_b32_e32 v8, 0x1f8, v1
	v_and_b32_e32 v1, 64, v188
	v_add_u32_e32 v1, 64, v1
	v_xor_b32_e32 v2, 32, v188
	v_cmp_lt_i32_e32 vcc, v2, v1
	s_load_dwordx4 s[24:27], s[0:1], 0x38
	v_readlane_b32 s13, v254, 60
	v_cndmask_b32_e32 v2, v188, v2, vcc
	v_lshlrev_b32_e32 v22, 2, v2
	v_xor_b32_e32 v2, 16, v188
	v_cmp_lt_i32_e32 vcc, v2, v1
	s_mul_i32 s13, s13, 3
	s_mov_b32 s23, s12
	v_cndmask_b32_e32 v2, v188, v2, vcc
	v_lshlrev_b32_e32 v23, 2, v2
	v_xor_b32_e32 v2, 8, v188
	v_cmp_lt_i32_e32 vcc, v2, v1
	s_add_i32 s22, s13, 1
	s_lshl_b64 s[22:23], s[22:23], 12
	v_cndmask_b32_e32 v2, v188, v2, vcc
	v_lshlrev_b32_e32 v24, 2, v2
	v_xor_b32_e32 v2, 4, v188
	v_cmp_lt_i32_e32 vcc, v2, v1
	s_waitcnt lgkmcnt(0)
	s_add_u32 s26, s26, s22
	s_addc_u32 s27, s27, s23
	v_cndmask_b32_e32 v2, v188, v2, vcc
	v_lshlrev_b32_e32 v25, 2, v2
	v_xor_b32_e32 v2, 2, v188
	v_cmp_lt_i32_e32 vcc, v2, v1
	s_add_u32 s22, s24, s22
	s_addc_u32 s23, s25, s23
	v_cndmask_b32_e32 v2, v188, v2, vcc
	v_lshlrev_b32_e32 v26, 2, v2
	v_xor_b32_e32 v2, 1, v188
	v_cmp_lt_i32_e32 vcc, v2, v1
	v_lshlrev_b32_e32 v16, 2, v8
	v_lshl_add_u64 v[4:5], s[26:27], 0, v[16:17]
	v_cndmask_b32_e32 v1, v188, v2, vcc
	v_lshlrev_b32_e32 v27, 2, v1
	v_ashrrev_i32_e32 v1, 31, v0
	v_lshlrev_b64 v[6:7], 10, v[0:1]
	v_or_b32_e32 v6, v6, v8
	v_lshlrev_b64 v[8:9], 11, v[0:1]
	v_and_b32_e32 v1, 63, v10
	v_lshl_add_u64 v[2:3], s[22:23], 0, v[16:17]
	v_lshl_or_b32 v8, v1, 4, v8
	s_mov_b64 s[22:23], 0
	global_load_dwordx4 v[214:217], v[2:3], off offset:16
	global_load_dwordx4 v[218:221], v[2:3], off
	global_load_dwordx4 v[222:225], v[4:5], off offset:16
	global_load_dwordx4 v[226:229], v[4:5], off
	global_load_dwordx4 v[230:233], v[2:3], off offset:2064
	global_load_dwordx4 v[234:237], v[2:3], off offset:2048
	global_load_dwordx4 v[238:241], v[4:5], off offset:2064
	global_load_dwordx4 v[242:245], v[4:5], off offset:2048
	s_waitcnt vmcnt(0)
.LBB0_96:
	v_lshl_add_u64 v[18:19], s[2:3], 0, v[8:9]
	v_add_co_u32_e32 v10, vcc, 0xfd80000, v18
	v_add_u32_e32 v0, s60, v0
	s_nop 0
	v_addc_co_u32_e32 v11, vcc, 0, v19, vcc
	v_add_co_u32_e32 v28, vcc, 0xb880000, v18
	global_load_dwordx4 v[12:15], v[10:11], off
	s_nop 0
	v_addc_co_u32_e32 v29, vcc, 0, v19, vcc
	v_add_co_u32_e32 v40, vcc, 0xdb00000, v18
	global_load_dwordx4 v[32:35], v[28:29], off
	s_nop 0
	v_addc_co_u32_e32 v41, vcc, 0, v19, vcc
	global_load_dwordx4 v[36:39], v[40:41], off
	global_load_dwordx4 v[202:205], v[10:11], off offset:1024
	global_load_dwordx4 v[206:209], v[28:29], off offset:1024
	global_load_dwordx4 v[210:213], v[40:41], off offset:1024
	v_lshl_add_u64 v[8:9], v[8:9], 0, s[44:45]
	s_waitcnt vmcnt(3)
	v_lshlrev_b32_e32 v1, 16, v12
	v_lshlrev_b32_e32 v16, 16, v32
	v_lshlrev_b32_e32 v18, 16, v36
	v_add_f32_e32 v18, v18, v16
	v_fmac_f32_e32 v18, 0x3fd744fd, v1
	v_and_b32_e32 v1, 0xffff0000, v12
	v_and_b32_e32 v12, 0xffff0000, v36
	v_and_b32_e32 v16, 0xffff0000, v32
	v_add_f32_e32 v19, v12, v16
	v_lshlrev_b32_e32 v12, 16, v33
	v_lshlrev_b32_e32 v16, 16, v37
	v_fmac_f32_e32 v19, 0x3fd744fd, v1
	v_lshlrev_b32_e32 v1, 16, v13
	v_add_f32_e32 v20, v16, v12
	v_fmac_f32_e32 v20, 0x3fd744fd, v1
	v_and_b32_e32 v1, 0xffff0000, v13
	v_and_b32_e32 v12, 0xffff0000, v37
	v_and_b32_e32 v13, 0xffff0000, v33
	v_add_f32_e32 v21, v12, v13
	v_lshlrev_b32_e32 v12, 16, v34
	v_lshlrev_b32_e32 v13, 16, v38
	v_fmac_f32_e32 v21, 0x3fd744fd, v1
	v_lshlrev_b32_e32 v1, 16, v14
	v_add_f32_e32 v31, v13, v12
	v_and_b32_e32 v12, 0xffff0000, v38
	v_and_b32_e32 v13, 0xffff0000, v34
	v_fmac_f32_e32 v31, 0x3fd744fd, v1
	v_and_b32_e32 v1, 0xffff0000, v14
	v_add_f32_e32 v32, v12, v13
	v_lshlrev_b32_e32 v12, 16, v35
	v_lshlrev_b32_e32 v13, 16, v39
	v_fmac_f32_e32 v32, 0x3fd744fd, v1
	v_lshlrev_b32_e32 v1, 16, v15
	v_add_f32_e32 v33, v13, v12
	v_and_b32_e32 v12, 0xffff0000, v39
	v_and_b32_e32 v13, 0xffff0000, v35
	v_fmac_f32_e32 v33, 0x3fd744fd, v1
	v_and_b32_e32 v1, 0xffff0000, v15
	v_add_f32_e32 v34, v12, v13
	s_nop 0
	v_add_f32_e32 v30, 0, v18
	v_add_f32_e32 v30, v19, v30
	v_fmac_f32_e32 v34, 0x3fd744fd, v1
	v_add_f32_e32 v30, v20, v30
	v_add_f32_e32 v30, v21, v30
	v_add_f32_e32 v30, v31, v30
	v_add_f32_e32 v30, v32, v30
	v_add_f32_e32 v30, v33, v30
	v_add_f32_e32 v30, v34, v30
	s_waitcnt vmcnt(2)
	v_lshlrev_b32_e32 v16, 16, v202
	s_waitcnt vmcnt(1)
	v_lshlrev_b32_e32 v1, 16, v206
	s_waitcnt vmcnt(0)
; __device__ __forceinline__ void ln_phase(ArgsP a_, int lnidx, float cs, bool final_) { const ArgsP a = a_;
;     ...
;             for (int e = 0; e < 4; ++e) { const unsigned hh = h[e], a0 = p0[e], a1 = p1[e];
;                 z[q * 8 + 2 * e] = __uint_as_float(hh << 16) * ALPHA + (__uint_as_float(a0 << 16) + __uint_as_float(a1 << 16)) * cs;
;                 z[q * 8 + 2 * e + 1] = __uint_as_float(hh & 0xffff0000u) * ALPHA + (__uint_as_float(a0 & 0xffff0000u) + __uint_as_float(a1 & 0xffff0000u)) * cs; } }
; #pragma unroll
;         for (int e = 0; e < 16; ++e) s += z[e];
;         const float mean = wave_sum(s) * (1.f / 1024.f); float v = 0.f;
; #pragma unroll
;         for (int e = 0; e < 16; ++e) { const float d = z[e] - mean; v += d * d; }
;         const float rstd = rsqrtf(wave_sum(v) * (1.f / 1024.f) + LN_EPS);
	v_lshlrev_b32_e32 v28, 16, v210
	v_add_f32_e32 v1, v28, v1
	v_fmac_f32_e32 v1, 0x3fd744fd, v16
	v_and_b32_e32 v16, 0xffff0000, v210
	v_and_b32_e32 v28, 0xffff0000, v206
	v_and_b32_e32 v12, 0xffff0000, v202
	v_add_f32_e32 v16, v16, v28
	v_lshlrev_b32_e32 v28, 16, v207
	v_lshlrev_b32_e32 v29, 16, v211
	v_fmac_f32_e32 v16, 0x3fd744fd, v12
	v_lshlrev_b32_e32 v12, 16, v203
	v_add_f32_e32 v28, v29, v28
	v_fmac_f32_e32 v28, 0x3fd744fd, v12
	v_and_b32_e32 v12, 0xffff0000, v203
	v_and_b32_e32 v13, 0xffff0000, v211
	v_and_b32_e32 v29, 0xffff0000, v207
	v_add_f32_e32 v29, v13, v29
	v_lshlrev_b32_e32 v41, 16, v213
	v_lshlrev_b32_e32 v45, 16, v209
	v_and_b32_e32 v40, 0xffff0000, v213
	v_and_b32_e32 v44, 0xffff0000, v209
	v_add_f32_e32 v30, v1, v30
	v_fmac_f32_e32 v29, 0x3fd744fd, v12
	v_lshlrev_b32_e32 v13, 16, v212
	v_lshlrev_b32_e32 v37, 16, v208
	v_and_b32_e32 v12, 0xffff0000, v212
	v_and_b32_e32 v36, 0xffff0000, v208
	v_add_f32_e32 v30, v16, v30
	v_and_b32_e32 v38, 0xffff0000, v205
	v_lshlrev_b32_e32 v39, 16, v205
	v_pk_add_f32 v[40:41], v[44:45], v[40:41]
	v_add_f32_e32 v30, v28, v30
	v_pk_fma_f32 v[38:39], v[38:39], s[34:35], v[40:41] op_sel_hi:[1,0,1]
	v_and_b32_e32 v40, 0xffff0000, v204
	v_lshlrev_b32_e32 v41, 16, v204
	v_pk_add_f32 v[12:13], v[36:37], v[12:13]
	v_add_f32_e32 v30, v29, v30
	v_pk_fma_f32 v[12:13], v[40:41], s[34:35], v[12:13] op_sel_hi:[1,0,1]
	s_nop 0
	v_add_f32_e32 v14, v13, v30
	v_add_f32_e32 v14, v12, v14
	v_add_f32_e32 v14, v39, v14
	v_add_f32_e32 v14, v38, v14
	ds_bpermute_b32 v15, v22, v14
	s_waitcnt lgkmcnt(0)
	v_add_f32_e32 v14, v14, v15
	ds_bpermute_b32 v15, v23, v14
	s_waitcnt lgkmcnt(0)
	v_add_f32_e32 v14, v14, v15
	ds_bpermute_b32 v15, v24, v14
	s_waitcnt lgkmcnt(0)
	v_add_f32_e32 v14, v14, v15
	ds_bpermute_b32 v15, v25, v14
	s_waitcnt lgkmcnt(0)
	v_add_f32_e32 v14, v14, v15
	ds_bpermute_b32 v15, v26, v14
	s_waitcnt lgkmcnt(0)
	v_add_f32_e32 v14, v14, v15
	ds_bpermute_b32 v15, v27, v14
	s_waitcnt lgkmcnt(0)
	v_add_f32_e32 v14, v14, v15
	v_fmac_f32_e32 v19, 0xba800000, v14
	v_fmac_f32_e32 v18, 0xba800000, v14
	v_mul_f32_e32 v35, v19, v19
	v_fmac_f32_e32 v35, v18, v18
	v_fmac_f32_e32 v20, 0xba800000, v14
	v_fmac_f32_e32 v35, v20, v20
	v_fmac_f32_e32 v21, 0xba800000, v14
	v_fmac_f32_e32 v35, v21, v21
	v_fmac_f32_e32 v31, 0xba800000, v14
	v_fmac_f32_e32 v35, v31, v31
	v_fmac_f32_e32 v32, 0xba800000, v14
	v_fmac_f32_e32 v35, v32, v32
	v_fmac_f32_e32 v33, 0xba800000, v14
	v_fmac_f32_e32 v35, v33, v33
	v_fmac_f32_e32 v34, 0xba800000, v14
	v_fmac_f32_e32 v35, v34, v34
	v_fmac_f32_e32 v1, 0xba800000, v14
	v_fmac_f32_e32 v35, v1, v1
	v_fmac_f32_e32 v16, 0xba800000, v14
	v_mul_f32_e32 v30, 0x3a800000, v14
	v_fmac_f32_e32 v35, v16, v16
	v_fmac_f32_e32 v28, 0xba800000, v14
	v_fmac_f32_e32 v35, v28, v28
	v_fmac_f32_e32 v29, 0xba800000, v14
	v_pk_add_f32 v[14:15], v[12:13], v[30:31] op_sel_hi:[1,0] neg_lo:[0,1] neg_hi:[0,1]
	v_fmac_f32_e32 v35, v29, v29
	v_pk_mul_f32 v[12:13], v[14:15], v[14:15]
	s_nop 0
	v_add_f32_e32 v13, v13, v35
	v_add_f32_e32 v35, v12, v13
	v_pk_add_f32 v[12:13], v[38:39], v[30:31] op_sel_hi:[1,0] neg_lo:[0,1] neg_hi:[0,1]
	s_nop 0
	v_pk_mul_f32 v[36:37], v[12:13], v[12:13]
	s_nop 0
	v_add_f32_e32 v30, v37, v35
	v_add_f32_e32 v30, v36, v30
	ds_bpermute_b32 v35, v22, v30
	s_waitcnt lgkmcnt(0)
	v_add_f32_e32 v30, v30, v35
	ds_bpermute_b32 v35, v23, v30
	s_waitcnt lgkmcnt(0)
	v_add_f32_e32 v30, v30, v35
	ds_bpermute_b32 v35, v24, v30
	s_waitcnt lgkmcnt(0)
	v_add_f32_e32 v30, v30, v35
	ds_bpermute_b32 v35, v25, v30
	s_waitcnt lgkmcnt(0)
	v_add_f32_e32 v30, v30, v35
	ds_bpermute_b32 v35, v26, v30
	s_waitcnt lgkmcnt(0)
; __device__ __forceinline__ unsigned cvt_pk_bf16(float lo, float hi) { unsigned r; asm("v_cvt_pk_bf16_f32 %0, %1, %2" : "=v"(r) : "v"(lo), "v"(hi)); return r; }
; __device__ __forceinline__ unsigned pk_fp8x4(float a, float b, float c, float d) { int w = 0; w = __builtin_amdgcn_cvt_pk_fp8_f32(clamp448(a), clamp448(b), w, false); w = __builtin_amdgcn_cvt_pk_fp8_f32(clamp448(c), clamp448(d), w, true); return (unsigned)w; }
; __device__ __forceinline__ void ln_phase(ArgsP a_, int lnidx, float cs, bool final_) { const ArgsP a = a_;
;     ...
;         const float rstd = rsqrtf(wave_sum(v) * (1.f / 1024.f) + LN_EPS);
;         float* yo = nullptr;
;         if (final_) { if (row < RP) { const int b = row / TP, t = row % TP; if (t >= 16) yo = a->out + O_YP + ((size_t)b * 2048 + t - 16) * 1024; } else yo = a->out + O_YS + (size_t)(row - RP) * 1024; }
; #pragma unroll
;         for (int q = 0; q < 2; ++q) { const int cc = q * 512 + lane * 8; const f32x4 g0 = *(const f32x4*)(g + cc), g1 = *(const f32x4*)(g + cc + 4), b0 = *(const f32x4*)(bb + cc), b1 = *(const f32x4*)(bb + cc + 4);
;             f32x4 o0, o1;
; #pragma unroll
;             for (int e = 0; e < 4; ++e) { o0[e] = (z[q * 8 + e] - mean) * rstd * g0[e] + b0[e]; o1[e] = (z[q * 8 + 4 + e] - mean) * rstd * g1[e] + b1[e]; }
;             if (final_) { if (yo) { *(f32x4*)(yo + cc) = o0; *(f32x4*)(yo + cc + 4) = o1; } }
;             else { *(u32x4*)(HB + (size_t)row * 1024 + cc) = (u32x4){cvt_pk_bf16(o0[0], o0[1]), cvt_pk_bf16(o0[2], o0[3]), cvt_pk_bf16(o1[0], o1[1]), cvt_pk_bf16(o1[2], o1[3])};
;                    *(u32x2*)(a->ws + B_HB8 + (size_t)row * 1024 + cc) = (u32x2){pk_fp8x4(o0[0] * SC_H, o0[1] * SC_H, o0[2] * SC_H, o0[3] * SC_H), pk_fp8x4(o1[0] * SC_H, o1[1] * SC_H, o1[2] * SC_H, o1[3] * SC_H)}; } }
	v_add_f32_e32 v30, v30, v35
	ds_bpermute_b32 v35, v27, v30
	s_waitcnt lgkmcnt(0)
	v_add_f32_e32 v30, v30, v35
	v_fmamk_f32 v30, v30, 0x3a800000, v187
	v_cmp_gt_f32_e32 vcc, s31, v30
	v_mul_f32_e32 v35, 0x4b800000, v30
	s_nop 0
	v_cndmask_b32_e32 v30, v30, v35, vcc
	v_rsq_f32_e32 v30, v30
	s_nop 0
	v_mul_f32_e32 v35, 0x45800000, v30
	v_cndmask_b32_e32 v30, v30, v35, vcc
	v_mul_f32_e32 v18, v18, v30
	v_mul_f32_e32 v15, v15, v30
	v_mul_f32_e32 v1, v1, v30
	v_mul_f32_e32 v14, v14, v30
	v_mul_f32_e32 v13, v13, v30
	v_mul_f32_e32 v12, v12, v30
	v_fma_f32 v35, v218, v18, v226
	v_mul_f32_e32 v18, v31, v30
	v_fma_f32 v31, v214, v18, v222
	v_mul_f32_e32 v18, v19, v30
	v_fma_f32 v36, v219, v18, v227
	v_mul_f32_e32 v18, v32, v30
	v_fma_f32 v32, v215, v18, v223
	v_mul_f32_e32 v18, v20, v30
	v_fma_f32 v37, v220, v18, v228
	v_mul_f32_e32 v18, v33, v30
	v_fma_f32 v33, v216, v18, v224
	v_mul_f32_e32 v18, v21, v30
	v_fma_f32 v51, v221, v18, v229
	v_mul_f32_e32 v18, v34, v30
	v_fma_f32 v47, v217, v18, v225
	v_cvt_pk_bf16_f32 v18, v35, v36
	v_cvt_pk_bf16_f32 v19, v37, v51
	v_cvt_pk_bf16_f32 v20, v31, v32
	v_cvt_pk_bf16_f32 v21, v33, v47
	global_store_dwordx4 v[10:11], v[18:21], off
	v_mul_f32_e32 v34, 0x4134cccd, v51
	s_nop 0
	v_mul_f32_e32 v18, 0x4134cccd, v35
	v_mul_f32_e32 v19, 0x4134cccd, v36
	v_med3_f32 v18, v18, s17, v190
	v_med3_f32 v19, v19, s17, v190
	v_mov_b32_e32 v20, v17
	v_cvt_pk_fp8_f32 v20, v18, v19
	v_mul_f32_e32 v21, 0x4134cccd, v37
	v_med3_f32 v18, v21, s17, v190
	v_med3_f32 v19, v34, s17, v190
	v_cvt_pk_fp8_f32 v20, v18, v19 op_sel:[0,0,1]
	v_mul_f32_e32 v18, 0x4134cccd, v31
	v_mul_f32_e32 v19, 0x4134cccd, v32
	v_med3_f32 v18, v18, s17, v190
	v_med3_f32 v19, v19, s17, v190
	v_mov_b32_e32 v21, v17
	v_cvt_pk_fp8_f32 v21, v18, v19
	v_mul_f32_e32 v31, 0x4134cccd, v33
	v_mul_f32_e32 v32, 0x4134cccd, v47
	v_med3_f32 v18, v31, s17, v190
	v_med3_f32 v19, v32, s17, v190
	v_cvt_pk_fp8_f32 v21, v18, v19 op_sel:[0,0,1]
	v_lshl_add_u64 v[18:19], s[2:3], 0, v[6:7]
	v_add_co_u32_e32 v18, vcc, s41, v18
	v_lshl_add_u64 v[6:7], v[6:7], 0, s[42:43]
	s_nop 0
	v_addc_co_u32_e32 v19, vcc, 0, v19, vcc
	global_store_dwordx2 v[18:19], v[20:21], off offset:1792
	v_cmp_lt_i32_e32 vcc, s40, v0
	s_or_b64 s[22:23], vcc, s[22:23]
	v_fma_f32 v20, v230, v15, v238
	v_mul_f32_e32 v15, v16, v30
	v_fma_f32 v1, v234, v1, v242
	v_fma_f32 v16, v235, v15, v243
	v_fma_f32 v21, v231, v14, v239
	v_mul_f32_e32 v14, v28, v30
	v_fma_f32 v31, v232, v13, v240
	v_mul_f32_e32 v13, v29, v30
	v_fma_f32 v28, v236, v14, v244
	v_fma_f32 v47, v237, v13, v245
	v_fma_f32 v43, v233, v12, v241
	v_cvt_pk_bf16_f32 v12, v1, v16
	v_cvt_pk_bf16_f32 v13, v28, v47
	v_cvt_pk_bf16_f32 v14, v20, v21
	v_cvt_pk_bf16_f32 v15, v31, v43
	global_store_dwordx4 v[10:11], v[12:15], off offset:1024
	v_mul_f32_e32 v1, 0x4134cccd, v1
	v_mul_f32_e32 v10, 0x4134cccd, v16
	v_med3_f32 v1, v1, s17, v190
	v_med3_f32 v13, v10, s17, v190
	v_mov_b32_e32 v10, v17
	v_cvt_pk_fp8_f32 v10, v1, v13
	v_mul_f32_e32 v11, 0x4134cccd, v28
	v_mul_f32_e32 v12, 0x4134cccd, v47
	v_med3_f32 v1, v11, s17, v190
	v_med3_f32 v11, v12, s17, v190
	v_cvt_pk_fp8_f32 v10, v1, v11 op_sel:[0,0,1]
	v_mul_f32_e32 v1, 0x4134cccd, v20
	v_mul_f32_e32 v11, 0x4134cccd, v21
	v_med3_f32 v1, v1, s17, v190
	v_med3_f32 v14, v11, s17, v190
	v_mov_b32_e32 v11, v17
	v_cvt_pk_fp8_f32 v11, v1, v14
	v_mul_f32_e32 v12, 0x4134cccd, v31
	v_mul_f32_e32 v13, 0x4134cccd, v43
	v_med3_f32 v1, v12, s17, v190
	v_med3_f32 v12, v13, s17, v190
	v_cvt_pk_fp8_f32 v11, v1, v12 op_sel:[0,0,1]
	global_store_dwordx2 v[18:19], v[10:11], off offset:2304
	s_andn2_b64 exec, exec, s[22:23]
	s_cbranch_execnz .LBB0_96

; __device__ __forceinline__ int TID() { int t = threadIdx.x; asm volatile("" : "+v"(t)); return t; }
; __device__ __forceinline__ int BID() { int t = blockIdx.x; asm volatile("" : "+s"(t)); return t; }
; __device__ __forceinline__ void ln_phase(ArgsP a_, int lnidx, float cs, bool final_) { const ArgsP a = a_;
;     const int lane = TID() & 63, wv = TID() >> 6; const int gw = BID() * 8 + wv, nw = gridDim.x * 8;
;     bf16_t* HB = (bf16_t*)(a->ws + B_HB); const bf16_t* P0 = (const bf16_t*)(a->ws + B_PARTB); const bf16_t* P1 = P0 + (size_t)MP * 1024;
;     const float* g = AIN(7) + (size_t)lnidx * 1024; const float* bb = AIN(8) + (size_t)lnidx * 1024;
;     for (int row = gw; row < M_; row += nw) {
;         float z[16]; float s = 0.f;
; #pragma unroll
;         for (int q = 0; q < 2; ++q) { const size_t o = (size_t)row * 1024 + q * 512 + lane * 8; const u32x4 h = *(const u32x4*)(HB + o), p0 = *(const u32x4*)(P0 + o), p1 = *(const u32x4*)(P1 + o);
; #pragma unroll
;             for (int e = 0; e < 4; ++e) { const unsigned hh = h[e], a0 = p0[e], a1 = p1[e];
;                 z[q * 8 + 2 * e] = __uint_as_float(hh << 16) * ALPHA + (__uint_as_float(a0 << 16) + __uint_as_float(a1 << 16)) * cs;
;                 z[q * 8 + 2 * e + 1] = __uint_as_float(hh & 0xffff0000u) * ALPHA + (__uint_as_float(a0 & 0xffff0000u) + __uint_as_float(a1 & 0xffff0000u)) * cs; } }
.LBB0_766:
	s_andn2_b64 vcc, exec, s[4:5]
	s_mov_b64 s[4:5], 0
	v_readlane_b32 s83, v254, 61
	s_cbranch_vccnz .LBB0_773
	v_readlane_b32 s18, v255, 1
	s_cmp_gt_i32 s83, 0
	s_mov_b64 s[4:5], -1
	s_mov_b32 s34, 0x3752b000
	v_readlane_b32 s68, v255, 3
	v_readlane_b32 s19, v255, 2
	s_cbranch_scc0 .LBB0_775
	s_cmp_gt_i32 s83, 1
	s_mov_b64 s[18:19], -1
	s_cbranch_scc0 .LBB0_1032
	v_mov_b32_e32 v10, v186
	v_mov_b32_e32 v0, v186
	s_mov_b32 s4, s93
	v_ashrrev_i32_e32 v0, 6, v0
	s_nop 0
	v_lshl_add_u32 v0, s4, 3, v0
	s_movk_i32 s4, 0x4480
	v_cmp_gt_i32_e32 vcc, s4, v0
	s_and_saveexec_b64 s[4:5], vcc
	s_mov_b32 s22, 0x3fd744fd
	v_readlane_b32 s40, v254, 49
	v_readlane_b32 s42, v254, 51
	s_mov_b32 s23, 0.5
	s_movk_i32 s13, 0x447f
	v_readlane_b32 s41, v254, 50
	v_readlane_b32 s43, v254, 52
	s_cbranch_execz .LBB0_772
	v_lshlrev_b32_e32 v1, 3, v10
	v_and_b32_e32 v8, 0x1f8, v1
	v_and_b32_e32 v1, 64, v188
	v_add_u32_e32 v1, 64, v1
	v_xor_b32_e32 v2, 32, v188
	v_cmp_lt_i32_e32 vcc, v2, v1
	s_load_dwordx4 s[24:27], s[0:1], 0x38
	v_readlane_b32 s0, v254, 60
	v_cndmask_b32_e32 v2, v188, v2, vcc
	v_lshlrev_b32_e32 v22, 2, v2
	v_xor_b32_e32 v2, 16, v188
	v_cmp_lt_i32_e32 vcc, v2, v1
	s_mul_i32 s0, s0, 3
	s_mov_b32 s1, s12
	v_cndmask_b32_e32 v2, v188, v2, vcc
	v_lshlrev_b32_e32 v23, 2, v2
	v_xor_b32_e32 v2, 8, v188
	v_cmp_lt_i32_e32 vcc, v2, v1
	s_lshl_b64 s[0:1], s[0:1], 12
	s_waitcnt lgkmcnt(0)
	s_add_u32 s18, s26, s0
	v_cndmask_b32_e32 v2, v188, v2, vcc
	v_lshlrev_b32_e32 v24, 2, v2
	v_xor_b32_e32 v2, 4, v188
	v_cmp_lt_i32_e32 vcc, v2, v1
	s_addc_u32 s19, s27, s1
	s_add_u32 s0, s24, s0
	v_cndmask_b32_e32 v2, v188, v2, vcc
	v_lshlrev_b32_e32 v25, 2, v2
	v_xor_b32_e32 v2, 2, v188
	v_cmp_lt_i32_e32 vcc, v2, v1
	s_addc_u32 s1, s25, s1
	v_lshlrev_b32_e32 v16, 2, v8
	v_cndmask_b32_e32 v2, v188, v2, vcc
	v_lshlrev_b32_e32 v26, 2, v2
	v_xor_b32_e32 v2, 1, v188
	v_cmp_lt_i32_e32 vcc, v2, v1
	v_lshl_add_u64 v[4:5], s[18:19], 0, v[16:17]
	s_nop 0
	v_cndmask_b32_e32 v1, v188, v2, vcc
	v_lshlrev_b32_e32 v27, 2, v1
	v_ashrrev_i32_e32 v1, 31, v0
	v_lshlrev_b64 v[6:7], 10, v[0:1]
	v_or_b32_e32 v6, v6, v8
	v_lshlrev_b64 v[8:9], 11, v[0:1]
	v_and_b32_e32 v1, 63, v10
	v_lshl_add_u64 v[2:3], s[0:1], 0, v[16:17]
	v_lshl_or_b32 v8, v1, 4, v8
	s_mov_b64 s[0:1], 0
	global_load_dwordx4 v[214:217], v[2:3], off offset:16
	global_load_dwordx4 v[218:221], v[2:3], off
	global_load_dwordx4 v[222:225], v[4:5], off offset:16
	global_load_dwordx4 v[226:229], v[4:5], off
	global_load_dwordx4 v[230:233], v[2:3], off offset:2064
	global_load_dwordx4 v[234:237], v[2:3], off offset:2048
	global_load_dwordx4 v[238:241], v[4:5], off offset:2064
	global_load_dwordx4 v[242:245], v[4:5], off offset:2048
	s_waitcnt vmcnt(0)
.LBB0_771:
	v_lshl_add_u64 v[18:19], s[2:3], 0, v[8:9]
	v_add_co_u32_e32 v10, vcc, 0xfd80000, v18
	v_add_u32_e32 v0, s60, v0
	s_nop 0
	v_addc_co_u32_e32 v11, vcc, 0, v19, vcc
	v_add_co_u32_e32 v28, vcc, 0xb880000, v18
	global_load_dwordx4 v[12:15], v[10:11], off
	s_nop 0
	v_addc_co_u32_e32 v29, vcc, 0, v19, vcc
	v_add_co_u32_e32 v40, vcc, 0xdb00000, v18
	global_load_dwordx4 v[32:35], v[28:29], off
	s_nop 0
	v_addc_co_u32_e32 v41, vcc, 0, v19, vcc
	global_load_dwordx4 v[36:39], v[40:41], off
	global_load_dwordx4 v[202:205], v[10:11], off offset:1024
	global_load_dwordx4 v[206:209], v[28:29], off offset:1024
	global_load_dwordx4 v[210:213], v[40:41], off offset:1024
	v_lshl_add_u64 v[8:9], v[8:9], 0, s[42:43]
	s_waitcnt vmcnt(3)
	v_lshlrev_b32_e32 v18, 16, v12
	v_and_b32_e32 v20, 0xffff0000, v12
	v_and_b32_e32 v30, 0xffff0000, v32
	v_lshlrev_b32_e32 v16, 16, v32
	v_lshlrev_b32_e32 v12, 16, v33
	v_and_b32_e32 v31, 0xffff0000, v36
	v_lshlrev_b32_e32 v1, 16, v36
	v_pk_add_f32 v[30:31], v[30:31], v[30:31] op_sel_hi:[0,1]
	v_add_f32_e32 v19, v16, v1
	v_mov_b32_e32 v21, v31
	v_and_b32_e32 v31, 0xffff0000, v37
	v_and_b32_e32 v30, 0xffff0000, v33
	v_pk_mul_f32 v[18:19], v[18:19], s[22:23]
	v_pk_mul_f32 v[20:21], v[20:21], s[22:23]
	v_lshlrev_b32_e32 v1, 16, v37
	v_pk_add_f32 v[30:31], v[30:31], v[30:31] op_sel_hi:[0,1]
	v_add_f32_e32 v18, v18, v19
	v_add_f32_e32 v19, v20, v21
	v_lshlrev_b32_e32 v20, 16, v13
	v_add_f32_e32 v21, v12, v1
	v_and_b32_e32 v12, 0xffff0000, v13
	v_mov_b32_e32 v13, v31
	v_pk_mul_f32 v[20:21], v[20:21], s[22:23]
	v_pk_mul_f32 v[12:13], v[12:13], s[22:23]
	v_add_f32_e32 v20, v20, v21
	v_add_f32_e32 v21, v12, v13
	v_lshlrev_b32_e32 v1, 16, v38
	v_lshlrev_b32_e32 v13, 16, v34
	v_lshlrev_b32_e32 v12, 16, v14
	v_add_f32_e32 v13, v13, v1
	v_and_b32_e32 v33, 0xffff0000, v38
	v_and_b32_e32 v32, 0xffff0000, v34
	v_pk_mul_f32 v[12:13], v[12:13], s[22:23]
	v_pk_add_f32 v[32:33], v[32:33], v[32:33] op_sel_hi:[0,1]
	v_add_f32_e32 v31, v12, v13
	v_and_b32_e32 v12, 0xffff0000, v14
	v_mov_b32_e32 v13, v33
	v_pk_mul_f32 v[12:13], v[12:13], s[22:23]
	v_lshlrev_b32_e32 v1, 16, v39
	v_add_f32_e32 v32, v12, v13
	v_lshlrev_b32_e32 v13, 16, v35
	v_lshlrev_b32_e32 v12, 16, v15
	v_add_f32_e32 v13, v13, v1
	v_pk_mul_f32 v[12:13], v[12:13], s[22:23]
	v_and_b32_e32 v14, 0xffff0000, v35
	v_add_f32_e32 v33, v12, v13
	v_and_b32_e32 v12, 0xffff0000, v15
	v_and_b32_e32 v15, 0xffff0000, v39
	v_pk_add_f32 v[14:15], v[14:15], v[14:15] op_sel_hi:[0,1]
	v_mov_b32_e32 v13, v15
	v_pk_mul_f32 v[12:13], v[12:13], s[22:23]
	s_nop 0
	v_add_f32_e32 v34, v12, v13
	s_nop 0
	s_waitcnt vmcnt(2)
	v_lshlrev_b32_e32 v28, 16, v202
	s_waitcnt vmcnt(1)
	v_lshlrev_b32_e32 v16, 16, v206
	s_waitcnt vmcnt(0)
; __device__ __forceinline__ void ln_phase(ArgsP a_, int lnidx, float cs, bool final_) { const ArgsP a = a_;
;     ...
;             for (int e = 0; e < 4; ++e) { const unsigned hh = h[e], a0 = p0[e], a1 = p1[e];
;                 z[q * 8 + 2 * e] = __uint_as_float(hh << 16) * ALPHA + (__uint_as_float(a0 << 16) + __uint_as_float(a1 << 16)) * cs;
;                 z[q * 8 + 2 * e + 1] = __uint_as_float(hh & 0xffff0000u) * ALPHA + (__uint_as_float(a0 & 0xffff0000u) + __uint_as_float(a1 & 0xffff0000u)) * cs; } }
; #pragma unroll
;         for (int e = 0; e < 16; ++e) s += z[e];
;         const float mean = wave_sum(s) * (1.f / 1024.f); float v = 0.f;
; #pragma unroll
;         for (int e = 0; e < 16; ++e) { const float d = z[e] - mean; v += d * d; }
;         const float rstd = rsqrtf(wave_sum(v) * (1.f / 1024.f) + LN_EPS);
	v_lshlrev_b32_e32 v1, 16, v210
	v_add_f32_e32 v29, v16, v1
	v_and_b32_e32 v45, 0xffff0000, v210
	v_and_b32_e32 v44, 0xffff0000, v206
	v_pk_mul_f32 v[28:29], v[28:29], s[22:23]
	v_pk_add_f32 v[44:45], v[44:45], v[44:45] op_sel_hi:[0,1]
	v_add_f32_e32 v1, v28, v29
	v_and_b32_e32 v28, 0xffff0000, v202
	v_mov_b32_e32 v29, v45
	v_pk_mul_f32 v[28:29], v[28:29], s[22:23]
	v_lshlrev_b32_e32 v12, 16, v211
	v_and_b32_e32 v41, 0xffff0000, v211
	v_and_b32_e32 v40, 0xffff0000, v207
	v_add_f32_e32 v16, v28, v29
	v_lshlrev_b32_e32 v29, 16, v207
	v_pk_add_f32 v[36:37], v[40:41], v[40:41] op_sel_hi:[0,1]
	v_lshlrev_b32_e32 v28, 16, v203
	v_add_f32_e32 v29, v29, v12
	v_and_b32_e32 v12, 0xffff0000, v203
	v_mov_b32_e32 v13, v37
	v_pk_mul_f32 v[28:29], v[28:29], s[22:23]
	v_pk_mul_f32 v[12:13], v[12:13], s[22:23]
	v_add_f32_e32 v28, v28, v29
	v_add_f32_e32 v29, v12, v13
	v_lshlrev_b32_e32 v13, 16, v212
	v_lshlrev_b32_e32 v30, 16, v208
	v_and_b32_e32 v41, 0xffff0000, v212
	v_and_b32_e32 v40, 0xffff0000, v208
	v_lshlrev_b32_e32 v12, 16, v204
	v_add_f32_e32 v13, v30, v13
	v_and_b32_e32 v36, 0xffff0000, v204
	v_pk_add_f32 v[40:41], v[40:41], v[40:41] op_sel_hi:[0,1]
	v_lshlrev_b32_e32 v14, 16, v213
	v_lshlrev_b32_e32 v30, 16, v209
	v_mov_b32_e32 v37, v41
	v_add_f32_e32 v41, v30, v14
	v_add_f32_e32 v30, 0, v18
	v_add_f32_e32 v30, v19, v30
	v_add_f32_e32 v30, v20, v30
	v_add_f32_e32 v30, v21, v30
	v_add_f32_e32 v30, v31, v30
	v_add_f32_e32 v30, v32, v30
	v_and_b32_e32 v43, 0xffff0000, v213
	v_and_b32_e32 v42, 0xffff0000, v209
	v_add_f32_e32 v30, v33, v30
	v_pk_add_f32 v[38:39], v[42:43], v[42:43] op_sel_hi:[0,1]
	v_add_f32_e32 v30, v34, v30
	v_lshlrev_b32_e32 v40, 16, v205
	v_and_b32_e32 v14, 0xffff0000, v205
	v_mov_b32_e32 v15, v39
	v_add_f32_e32 v30, v1, v30
	v_pk_mul_f32 v[12:13], v[12:13], s[22:23]
	v_pk_mul_f32 v[36:37], v[36:37], s[22:23]
	v_pk_mul_f32 v[40:41], v[40:41], s[22:23]
	v_pk_mul_f32 v[14:15], v[14:15], s[22:23]
	v_add_f32_e32 v30, v16, v30
	v_add_f32_e32 v30, v28, v30
	v_mov_b32_e32 v38, v14
	v_mov_b32_e32 v39, v40
	v_mov_b32_e32 v40, v15
	v_mov_b32_e32 v14, v36
	v_mov_b32_e32 v15, v12
	v_mov_b32_e32 v12, v37
	v_add_f32_e32 v30, v29, v30
	v_pk_add_f32 v[12:13], v[14:15], v[12:13]
	v_pk_add_f32 v[38:39], v[38:39], v[40:41]
	v_add_f32_e32 v14, v13, v30
	v_add_f32_e32 v14, v12, v14
	v_add_f32_e32 v14, v39, v14
	v_add_f32_e32 v14, v38, v14
	ds_bpermute_b32 v15, v22, v14
	s_waitcnt lgkmcnt(0)
	v_add_f32_e32 v14, v14, v15
	ds_bpermute_b32 v15, v23, v14
	s_waitcnt lgkmcnt(0)
	v_add_f32_e32 v14, v14, v15
	ds_bpermute_b32 v15, v24, v14
	s_waitcnt lgkmcnt(0)
	v_add_f32_e32 v14, v14, v15
	ds_bpermute_b32 v15, v25, v14
	s_waitcnt lgkmcnt(0)
	v_add_f32_e32 v14, v14, v15
	ds_bpermute_b32 v15, v26, v14
	s_waitcnt lgkmcnt(0)
	v_add_f32_e32 v14, v14, v15
	ds_bpermute_b32 v15, v27, v14
	s_waitcnt lgkmcnt(0)
	v_add_f32_e32 v14, v14, v15
	v_fmac_f32_e32 v19, 0xba800000, v14
	v_fmac_f32_e32 v18, 0xba800000, v14
	v_mul_f32_e32 v35, v19, v19
	v_fmac_f32_e32 v35, v18, v18
	v_fmac_f32_e32 v20, 0xba800000, v14
	v_fmac_f32_e32 v35, v20, v20
	v_fmac_f32_e32 v21, 0xba800000, v14
	v_fmac_f32_e32 v35, v21, v21
	v_fmac_f32_e32 v31, 0xba800000, v14
	v_fmac_f32_e32 v35, v31, v31
	v_fmac_f32_e32 v32, 0xba800000, v14
	v_fmac_f32_e32 v35, v32, v32
	v_fmac_f32_e32 v33, 0xba800000, v14
	v_fmac_f32_e32 v35, v33, v33
	v_fmac_f32_e32 v34, 0xba800000, v14
	v_fmac_f32_e32 v35, v34, v34
	v_fmac_f32_e32 v1, 0xba800000, v14
	v_fmac_f32_e32 v35, v1, v1
	v_fmac_f32_e32 v16, 0xba800000, v14
	v_mul_f32_e32 v30, 0x3a800000, v14
	v_fmac_f32_e32 v35, v16, v16
	v_fmac_f32_e32 v28, 0xba800000, v14
	v_fmac_f32_e32 v35, v28, v28
	v_fmac_f32_e32 v29, 0xba800000, v14
	v_pk_add_f32 v[14:15], v[12:13], v[30:31] op_sel_hi:[1,0] neg_lo:[0,1] neg_hi:[0,1]
	v_fmac_f32_e32 v35, v29, v29
	v_pk_mul_f32 v[12:13], v[14:15], v[14:15]
	s_nop 0
	v_add_f32_e32 v13, v13, v35
	v_add_f32_e32 v35, v12, v13
	v_pk_add_f32 v[12:13], v[38:39], v[30:31] op_sel_hi:[1,0] neg_lo:[0,1] neg_hi:[0,1]
	s_nop 0
	v_pk_mul_f32 v[36:37], v[12:13], v[12:13]
	s_nop 0
	v_add_f32_e32 v30, v37, v35
	v_add_f32_e32 v30, v36, v30
	ds_bpermute_b32 v35, v22, v30
	s_waitcnt lgkmcnt(0)
; __device__ __forceinline__ unsigned cvt_pk_bf16(float lo, float hi) { unsigned r; asm("v_cvt_pk_bf16_f32 %0, %1, %2" : "=v"(r) : "v"(lo), "v"(hi)); return r; }
; __device__ __forceinline__ unsigned pk_fp8x4(float a, float b, float c, float d) { int w = 0; w = __builtin_amdgcn_cvt_pk_fp8_f32(clamp448(a), clamp448(b), w, false); w = __builtin_amdgcn_cvt_pk_fp8_f32(clamp448(c), clamp448(d), w, true); return (unsigned)w; }
; __device__ __forceinline__ void ln_phase(ArgsP a_, int lnidx, float cs, bool final_) { const ArgsP a = a_;
;     ...
;         const float rstd = rsqrtf(wave_sum(v) * (1.f / 1024.f) + LN_EPS);
;         float* yo = nullptr;
;         if (final_) { if (row < RP) { const int b = row / TP, t = row % TP; if (t >= 16) yo = a->out + O_YP + ((size_t)b * 2048 + t - 16) * 1024; } else yo = a->out + O_YS + (size_t)(row - RP) * 1024; }
; #pragma unroll
;         for (int q = 0; q < 2; ++q) { const int cc = q * 512 + lane * 8; const f32x4 g0 = *(const f32x4*)(g + cc), g1 = *(const f32x4*)(g + cc + 4), b0 = *(const f32x4*)(bb + cc), b1 = *(const f32x4*)(bb + cc + 4);
;             f32x4 o0, o1;
; #pragma unroll
;             for (int e = 0; e < 4; ++e) { o0[e] = (z[q * 8 + e] - mean) * rstd * g0[e] + b0[e]; o1[e] = (z[q * 8 + 4 + e] - mean) * rstd * g1[e] + b1[e]; }
;             if (final_) { if (yo) { *(f32x4*)(yo + cc) = o0; *(f32x4*)(yo + cc + 4) = o1; } }
;             else { *(u32x4*)(HB + (size_t)row * 1024 + cc) = (u32x4){cvt_pk_bf16(o0[0], o0[1]), cvt_pk_bf16(o0[2], o0[3]), cvt_pk_bf16(o1[0], o1[1]), cvt_pk_bf16(o1[2], o1[3])};
;                    *(u32x2*)(a->ws + B_HB8 + (size_t)row * 1024 + cc) = (u32x2){pk_fp8x4(o0[0] * SC_H, o0[1] * SC_H, o0[2] * SC_H, o0[3] * SC_H), pk_fp8x4(o1[0] * SC_H, o1[1] * SC_H, o1[2] * SC_H, o1[3] * SC_H)}; } }
	v_add_f32_e32 v30, v30, v35
	ds_bpermute_b32 v35, v23, v30
	s_waitcnt lgkmcnt(0)
	v_add_f32_e32 v30, v30, v35
	ds_bpermute_b32 v35, v24, v30
	s_waitcnt lgkmcnt(0)
	v_add_f32_e32 v30, v30, v35
	ds_bpermute_b32 v35, v25, v30
	s_waitcnt lgkmcnt(0)
	v_add_f32_e32 v30, v30, v35
	ds_bpermute_b32 v35, v26, v30
	s_waitcnt lgkmcnt(0)
	v_add_f32_e32 v30, v30, v35
	ds_bpermute_b32 v35, v27, v30
	s_waitcnt lgkmcnt(0)
	v_add_f32_e32 v30, v30, v35
	v_fmamk_f32 v30, v30, 0x3a800000, v187
	v_cmp_gt_f32_e32 vcc, s31, v30
	v_mul_f32_e32 v35, 0x4b800000, v30
	s_nop 0
	v_cndmask_b32_e32 v30, v30, v35, vcc
	v_rsq_f32_e32 v30, v30
	s_nop 0
	v_mul_f32_e32 v35, 0x45800000, v30
	v_cndmask_b32_e32 v30, v30, v35, vcc
	v_mul_f32_e32 v18, v18, v30
	v_mul_f32_e32 v15, v15, v30
	v_mul_f32_e32 v1, v1, v30
	v_mul_f32_e32 v14, v14, v30
	v_mul_f32_e32 v13, v13, v30
	v_mul_f32_e32 v12, v12, v30
	v_fma_f32 v35, v218, v18, v226
	v_mul_f32_e32 v18, v31, v30
	v_fma_f32 v31, v214, v18, v222
	v_mul_f32_e32 v18, v19, v30
	v_fma_f32 v36, v219, v18, v227
	v_mul_f32_e32 v18, v32, v30
	v_fma_f32 v32, v215, v18, v223
	v_mul_f32_e32 v18, v20, v30
	v_fma_f32 v37, v220, v18, v228
	v_mul_f32_e32 v18, v33, v30
	v_fma_f32 v33, v216, v18, v224
	v_mul_f32_e32 v18, v21, v30
	v_fma_f32 v51, v221, v18, v229
	v_mul_f32_e32 v18, v34, v30
	v_fma_f32 v47, v217, v18, v225
	v_cvt_pk_bf16_f32 v18, v35, v36
	v_cvt_pk_bf16_f32 v19, v37, v51
	v_cvt_pk_bf16_f32 v20, v31, v32
	v_cvt_pk_bf16_f32 v21, v33, v47
	global_store_dwordx4 v[10:11], v[18:21], off
	v_mul_f32_e32 v34, 0x4134cccd, v51
	s_nop 0
	v_mul_f32_e32 v18, 0x4134cccd, v35
	v_mul_f32_e32 v19, 0x4134cccd, v36
	v_med3_f32 v18, v18, s17, v190
	v_med3_f32 v19, v19, s17, v190
	v_mov_b32_e32 v20, v17
	v_cvt_pk_fp8_f32 v20, v18, v19
	v_mul_f32_e32 v21, 0x4134cccd, v37
	v_med3_f32 v18, v21, s17, v190
	v_med3_f32 v19, v34, s17, v190
	v_cvt_pk_fp8_f32 v20, v18, v19 op_sel:[0,0,1]
	v_mul_f32_e32 v18, 0x4134cccd, v31
	v_mul_f32_e32 v19, 0x4134cccd, v32
	v_med3_f32 v18, v18, s17, v190
	v_med3_f32 v19, v19, s17, v190
	v_mov_b32_e32 v21, v17
	v_cvt_pk_fp8_f32 v21, v18, v19
	v_mul_f32_e32 v31, 0x4134cccd, v33
	v_mul_f32_e32 v32, 0x4134cccd, v47
	v_med3_f32 v18, v31, s17, v190
	v_med3_f32 v19, v32, s17, v190
	v_cvt_pk_fp8_f32 v21, v18, v19 op_sel:[0,0,1]
	v_lshl_add_u64 v[18:19], s[2:3], 0, v[6:7]
	v_add_co_u32_e32 v18, vcc, s34, v18
	v_lshl_add_u64 v[6:7], v[6:7], 0, s[40:41]
	s_nop 0
	v_addc_co_u32_e32 v19, vcc, 0, v19, vcc
	v_cmp_lt_i32_e32 vcc, s13, v0
	s_or_b64 s[0:1], vcc, s[0:1]
	v_fma_f32 v20, v230, v15, v238
	v_mul_f32_e32 v15, v16, v30
	v_fma_f32 v1, v234, v1, v242
	v_fma_f32 v16, v235, v15, v243
	v_fma_f32 v21, v231, v14, v239
	v_mul_f32_e32 v14, v28, v30
	v_fma_f32 v31, v232, v13, v240
	v_mul_f32_e32 v13, v29, v30
	v_fma_f32 v28, v236, v14, v244
	v_fma_f32 v47, v237, v13, v245
	v_fma_f32 v43, v233, v12, v241
	v_cvt_pk_bf16_f32 v12, v1, v16
	v_cvt_pk_bf16_f32 v13, v28, v47
	v_cvt_pk_bf16_f32 v14, v20, v21
	v_cvt_pk_bf16_f32 v15, v31, v43
	global_store_dwordx4 v[10:11], v[12:15], off offset:1024
	v_mul_f32_e32 v1, 0x4134cccd, v1
	v_mul_f32_e32 v10, 0x4134cccd, v16
	v_med3_f32 v1, v1, s17, v190
	v_med3_f32 v13, v10, s17, v190
	v_mov_b32_e32 v10, v17
	v_cvt_pk_fp8_f32 v10, v1, v13
	v_mul_f32_e32 v11, 0x4134cccd, v28
	v_mul_f32_e32 v12, 0x4134cccd, v47
	v_med3_f32 v1, v11, s17, v190
	v_med3_f32 v11, v12, s17, v190
	v_cvt_pk_fp8_f32 v10, v1, v11 op_sel:[0,0,1]
	v_mul_f32_e32 v1, 0x4134cccd, v20
	v_mul_f32_e32 v11, 0x4134cccd, v21
	v_med3_f32 v1, v1, s17, v190
	v_med3_f32 v14, v11, s17, v190
	v_mov_b32_e32 v11, v17
	v_cvt_pk_fp8_f32 v11, v1, v14
	v_mul_f32_e32 v12, 0x4134cccd, v31
	v_mul_f32_e32 v13, 0x4134cccd, v43
	v_med3_f32 v1, v12, s17, v190
	v_med3_f32 v12, v13, s17, v190
	v_cvt_pk_fp8_f32 v11, v1, v12 op_sel:[0,0,1]
	s_andn2_b64 exec, exec, s[0:1]
	s_cbranch_execnz .LBB0_771
